# attention main loop: next K tile loaded global->LDS directly (LDS-DMA, XOR swizzle applied on the source chunk) instead of via VGPRs + 2 ds_write_b128 per half-step
# speedup vs baseline: 1.0131x; 1.0014x over previous
; #define SBAR() __builtin_amdgcn_sched_barrier(0)
; __device__ __forceinline__ int v_st(int k, int c) { const int kk = (k & ~0xC) | ((k & 4) << 1) | ((k & 8) >> 1); return ((kk >> 3) * 4 + (c >> 5)) * 512 + ((kk & 7) * 32 + (c & 31)) * 2; }
; __device__ __forceinline__ void partialSM(f32x16& p0, f32x16& p1, float& m_reg, float& mn, float& alpha, bool rs) {
;     float pmax = p0[0]; for (int r = 1; r < 16; ++r) pmax = fmaxf(pmax, p0[r]); for (int r = 0; r < 16; ++r) pmax = fmaxf(pmax, p1[r]);
;     if (!rs) pmax = -__builtin_inff();
;     { auto rr = __builtin_amdgcn_permlane32_swap(__float_as_uint(pmax), __float_as_uint(pmax), false, false);
;       pmax = fmaxf(__uint_as_float(rr[0]), __uint_as_float(rr[1])); }
;     constexpr float C2 = 1.4426950408889634f * SCALE;
;     if (__builtin_expect(__all((pmax - m_reg) * SCALE <= THR), 1)) { mn = m_reg; alpha = 1.f; }
;     else { mn = fmaxf(m_reg, pmax); alpha = __builtin_amdgcn_exp2f((m_reg - mn) * C2); m_reg = mn; }
;     const float mnL = rs ? -mn * C2 : -__builtin_inff();
;     for (int r = 0; r < 16; ++r) p0[r] = fmaf(p0[r], C2, mnL); for (int r = 0; r < 16; ++r) p1[r] = fmaf(p1[r], C2, mnL);
;     for (int r = 0; r < 16; ++r) p0[r] = __builtin_amdgcn_exp2f(p0[r]);
; }
; __device__ __forceinline__ void moba_block(const BlockRef& cur, const BlockRef& nxt, char* lds, Seam& S) {
;     ...
;     const int qlo = cur.P0 + wid * QBLK, qm = qlo + r32 - 4 * hi;
;     char* V_lds = lds; char* K_lds = lds + 2 * SHM_V;
;     float* ws = (float*)(lds + 2 * SHM_V + 2 * SHM_K) + wid * 64; float* li_l = ws, * al_l = ws + 32;
;     float m_reg = -1e30f, l_reg = 0; f32x16 o[4] = {};
;     const int sr = tid >> 4, sc = (tid & 15) * 8, vst0 = v_st(sr, sc), vst1 = v_st(32 + sr, sc), kws = KSWZ(sr, sc * 2);
;     const int vb0 = (int)(uintptr_t)V_lds + v_rd_base(lane);
;     const bf16* Kh = cur.K; const bf16* Vh = cur.V;
;     const int qb = cur.qb;
;     const unsigned sel = gate_select(S.qr, lds, qb, r32, hi);
;     ...
;     constexpr int NQL = 8;
;     ...
;     f32x16 pA0, pA1, pB0, pB1; float mnA, mnB, alA, alB; bf16x8 pa0, pa1, pa2, pa3;
;     SWRITE_HV(0); SBAR();
;     if (NT > 1) { SLOAD_H(Kh, Vh, KBASE(1)); }
;     SBAR(); qkt<0>(pA0, pA1, K_lds, r32, hi, S.qr);
;     MASKT(pA0, pA1, 0); partialSM(pA0, pA1, m_reg, mnA, alA, RSEL(0));
;     if (NT > 1) { VMW(); SWRITE_H(1); }
;     __syncthreads();
.LBB0_88:
	s_and_b32 s0, s3, 0x3fffffc0
	v_and_b32_e32 v51, 63, v183
	s_lshl_b32 s0, s0, 2
	s_lshl_b32 s2, s44, 2
	s_add_i32 s0, s0, 0
	v_lshlrev_b32_e32 v52, 8, v166
	v_and_b32_e32 v53, 0x70, v183
	v_lshlrev_b32_e32 v54, 4, v51
	s_xor_b64 s[10:11], s[10:11], -1
	s_add_i32 s2, s2, 4
	s_add_i32 s7, s0, 0x10000
	v_bitop3_b32 v53, v98, v52, v53 bitop3:0xde
	v_lshlrev_b32_e32 v52, 3, v51
	v_and_b32_e32 v54, 0xc0, v54
	v_lshlrev_b32_e32 v55, 1, v51
	v_and_or_b32 v54, v52, 24, v54
	v_and_b32_e32 v55, 32, v55
	v_and_b32_e32 v52, 0x100, v52
	s_cmp_lg_u32 0, -1
	v_or3_b32 v52, v54, v55, v52
	s_cselect_b32 s0, 0, 0
	v_add_u32_e32 v185, s0, v52
	v_and_b32_e32 v52, 1, v165
	v_cmp_eq_u32_e32 vcc, 1, v52
	v_max_f32_e32 v52, v19, v19
	v_max_f32_e32 v54, v18, v18
	v_max_f32_e32 v52, v54, v52
	v_max3_f32 v52, v52, v20, v21
	v_max3_f32 v52, v52, v22, v23
	v_max3_f32 v52, v52, v24, v25
	v_max3_f32 v52, v52, v26, v27
	v_max3_f32 v52, v52, v28, v29
	v_max3_f32 v52, v52, v30, v31
	v_max3_f32 v52, v52, v32, v33
	v_max3_f32 v52, v52, v2, v3
	v_max3_f32 v52, v52, v4, v5
	v_max3_f32 v52, v52, v6, v7
	v_max3_f32 v52, v52, v8, v9
	v_max3_f32 v52, v52, v10, v11
	s_cmp_lt_i32 s44, 1
	v_max3_f32 v52, v52, v12, v13
	s_cselect_b64 s[0:1], -1, 0
	v_max3_f32 v52, v52, v14, v15
	v_max3_f32 v52, v52, v16, v17
	s_or_b64 vcc, s[0:1], vcc
	v_cndmask_b32_e32 v52, v220, v52, vcc
	v_mov_b32_e32 v54, v52
	s_nop 1
	v_permlane32_swap_b32_e32 v52, v54
	v_max_f32_e32 v54, v54, v54
	v_max_f32_e32 v52, v52, v52
	v_max_f32_e32 v52, v52, v54
	v_add_f32_e32 v54, 0x7149f2ca, v52
	v_mul_f32_e32 v54, 0x3db504f3, v54
	v_max_f32_e32 v52, 0xf149f2ca, v52
	v_cmp_ge_f32_e64 s[38:39], s91, v54
	v_sub_f32_e32 v54, 0xf149f2ca, v52
	v_mul_f32_e32 v54, 0x3e0293ee, v54
	s_cmp_eq_u64 s[38:39], exec
	v_exp_f32_e32 v54, v54
	s_cselect_b64 s[38:39], -1, 0
	v_mov_b32_e32 v55, 0xf149f2ca
	v_cndmask_b32_e64 v198, v52, v55, s[38:39]
	v_mul_f32_e32 v52, 0xbe0293ee, v198
	v_cndmask_b32_e32 v52, v220, v52, vcc
	v_cndmask_b32_e64 v196, v54, 1.0, s[38:39]
	v_mov_b32_e32 v54, v52
	v_fmamk_f32 v18, v18, 0x3e0293ee, v52
	v_fmamk_f32 v19, v19, 0x3e0293ee, v52
	v_fmamk_f32 v20, v20, 0x3e0293ee, v52
	v_fmamk_f32 v21, v21, 0x3e0293ee, v52
	v_fmamk_f32 v22, v22, 0x3e0293ee, v52
	v_fmamk_f32 v23, v23, 0x3e0293ee, v52
	v_fmamk_f32 v24, v24, 0x3e0293ee, v52
	v_fmamk_f32 v25, v25, 0x3e0293ee, v52
	v_fmamk_f32 v26, v26, 0x3e0293ee, v52
	v_fmamk_f32 v27, v27, 0x3e0293ee, v52
	v_fmamk_f32 v28, v28, 0x3e0293ee, v52
	v_fmamk_f32 v29, v29, 0x3e0293ee, v52
	v_fmamk_f32 v30, v30, 0x3e0293ee, v52
	v_fmamk_f32 v31, v31, 0x3e0293ee, v52
	v_fmamk_f32 v32, v32, 0x3e0293ee, v52
	v_fmac_f32_e32 v54, 0x3e0293ee, v33
	s_add_i32 s0, s6, 0xbfffff45
	v_pk_fma_f32 v[178:179], v[2:3], s[20:21], v[52:53] op_sel_hi:[1,0,0]
	v_exp_f32_e32 v231, v18
	v_exp_f32_e32 v233, v19
	v_exp_f32_e32 v229, v20
	v_exp_f32_e32 v232, v21
	v_exp_f32_e32 v228, v22
	v_exp_f32_e32 v230, v23
	v_exp_f32_e32 v226, v24
	v_exp_f32_e32 v227, v25
	v_exp_f32_e32 v223, v26
	v_exp_f32_e32 v225, v27
	v_exp_f32_e32 v209, v28
	v_exp_f32_e32 v224, v29
	v_exp_f32_e32 v206, v30
	v_exp_f32_e32 v208, v31
	v_exp_f32_e32 v205, v32
	v_exp_f32_e32 v207, v54
	v_add_u32_e32 v2, s0, v184
	s_waitcnt vmcnt(0)
	v_add_u32_e32 v188, 0, v53
	v_cmp_gt_u32_e64 s[38:39], 32, v51
	v_lshl_add_u32 v186, v50, 2, s7
	v_sub_u32_e32 v197, v2, v50
	v_mov_b32_e32 v50, v99
	v_mov_b32_e32 v51, v99
	v_pk_fma_f32 v[154:155], v[16:17], s[20:21], v[52:53] op_sel_hi:[1,0,0]
	v_pk_fma_f32 v[160:161], v[14:15], s[20:21], v[52:53] op_sel_hi:[1,0,0]
	v_pk_fma_f32 v[180:181], v[12:13], s[20:21], v[52:53] op_sel_hi:[1,0,0]
	v_pk_fma_f32 v[152:153], v[10:11], s[20:21], v[52:53] op_sel_hi:[1,0,0]
	v_pk_fma_f32 v[156:157], v[8:9], s[20:21], v[52:53] op_sel_hi:[1,0,0]
	v_pk_fma_f32 v[158:159], v[6:7], s[20:21], v[52:53] op_sel_hi:[1,0,0]
	v_pk_fma_f32 v[162:163], v[4:5], s[20:21], v[52:53] op_sel_hi:[1,0,0]
	s_waitcnt vmcnt(3)
	ds_write_b128 v191, v[34:37] offset:16384
	s_waitcnt vmcnt(2)
	ds_write_b128 v192, v[38:41] offset:16384
	s_waitcnt vmcnt(1)
	ds_write_b128 v188, v[42:45] offset:49152
	s_waitcnt vmcnt(0)
	ds_write_b128 v188, v[46:49] offset:57344
	v_mov_b32_e32 v52, v99
	v_mov_b32_e32 v53, v99
	v_mov_b32_e32 v54, v99
	v_mov_b32_e32 v55, v99
	v_mov_b32_e32 v56, v99
	v_mov_b32_e32 v57, v99
	v_mov_b32_e32 v58, v99
	v_mov_b32_e32 v59, v99
	v_mov_b32_e32 v60, v99
	v_mov_b32_e32 v61, v99
	v_mov_b32_e32 v62, v99
	v_mov_b32_e32 v63, v99
	v_mov_b32_e32 v64, v99
	v_mov_b32_e32 v65, v99
	v_mov_b64_e32 v[34:35], v[50:51]
	v_mov_b64_e32 v[18:19], v[50:51]
	v_mov_b64_e32 v[2:3], v[50:51]
	s_mov_b32 s3, 3
	v_lshl_add_u64 v[170:171], s[22:23], 0, v[98:99]
	v_lshl_add_u64 v[176:177], s[30:31], 0, v[98:99]
	v_lshl_add_u32 v187, v184, 2, s7
	v_mov_b32_e32 v189, 0
	s_movk_i32 s7, 0x7f
	v_mov_b64_e32 v[36:37], v[52:53]
	v_mov_b64_e32 v[38:39], v[54:55]
	v_mov_b64_e32 v[40:41], v[56:57]
	v_mov_b64_e32 v[42:43], v[58:59]
	v_mov_b64_e32 v[44:45], v[60:61]
	v_mov_b64_e32 v[46:47], v[62:63]
	v_mov_b64_e32 v[48:49], v[64:65]
	v_mov_b64_e32 v[20:21], v[52:53]
	v_mov_b64_e32 v[22:23], v[54:55]
	v_mov_b64_e32 v[24:25], v[56:57]
	v_mov_b64_e32 v[26:27], v[58:59]
	v_mov_b64_e32 v[28:29], v[60:61]
	v_mov_b64_e32 v[30:31], v[62:63]
	v_mov_b64_e32 v[32:33], v[64:65]
	v_mov_b64_e32 v[4:5], v[52:53]
	v_mov_b64_e32 v[6:7], v[54:55]
	v_mov_b64_e32 v[8:9], v[56:57]
	v_mov_b64_e32 v[10:11], v[58:59]
	v_mov_b64_e32 v[12:13], v[60:61]
	v_mov_b64_e32 v[14:15], v[62:63]
	v_mov_b64_e32 v[16:17], v[64:65]
	s_mov_b32 s100, 0
	v_readfirstlane_b32 s32, v0
	s_lshr_b32 s32, s32, 6
	s_lshl_b32 s32, s32, 10
	s_add_i32 s32, s32, 0x8000
	v_lshrrev_b32_e32 v236, 4, v0
	v_and_b32_e32 v236, 7, v236
	v_and_b32_e32 v237, 15, v0
	v_xor_b32_e32 v236, v236, v237
	v_sub_u32_e32 v236, v236, v237
	v_lshlrev_b32_e32 v236, 4, v236
	v_ashrrev_i32_e32 v237, 31, v236
	v_lshl_add_u64 v[234:235], v[176:177], 0, v[236:237]
	s_waitcnt lgkmcnt(0)
	s_barrier

; __device__ __forceinline__ void finishSM(f32x16& p0, f32x16& p1, float alpha, float& l_reg, bf16x8& pa0, bf16x8& pa1, bf16x8& pa2, bf16x8& pa3) {
;     for (int r = 0; r < 16; ++r) p1[r] = __builtin_amdgcn_exp2f(p1[r]);
;     float ps = 0; for (int r = 0; r < 16; ++r) ps += p0[r]; for (int r = 0; r < 16; ++r) ps += p1[r];
;     { auto rr = __builtin_amdgcn_permlane32_swap(__float_as_uint(ps), __float_as_uint(ps), false, false);
;       ps = __uint_as_float(rr[0]) + __uint_as_float(rr[1]); }
;     l_reg = l_reg * alpha + ps;
;     ...
;     PK4(p0, 0, pa0); PK4(p0, 8, pa1); PK4(p1, 0, pa2); PK4(p1, 8, pa3);
;     ...
; }
; template <int KB>
; __device__ __forceinline__ void qkt(f32x16& p0, f32x16& p1, const char* K_lds, int r32, int hi, const bf16x8* qr) {
;     p0 = f32x16{}; p1 = f32x16{};
;     const char* kb[4];
; #pragma unroll
;     for (int dd = 0; dd < 4; ++dd) kb[dd] = K_lds + KB * SHM_K + KSWZ(r32, (dd * 16 + hi * 8) * 2);
; #pragma unroll
;     for (int d0 = 0; d0 < 8; ++d0) { const char* a = kb[d0 & 3] + (d0 >> 2) * 128;
;         bf16x8 b0 = *reinterpret_cast<const bf16x8*>(a);
;         bf16x8 b1 = *reinterpret_cast<const bf16x8*>(a + 32 * 256);
;         p0 = __builtin_amdgcn_mfma_f32_32x32x16_bf16(b0, qr[d0], p0, 0, 0, 0);
;         p1 = __builtin_amdgcn_mfma_f32_32x32x16_bf16(b1, qr[d0], p1, 0, 0, 0); }
.Lmy_hs1_nov:
	s_mov_b32 s100, 0
	ds_read_b128 v[66:69], v169 offset:49152
	ds_read_b128 v[70:73], v169 offset:57344
	ds_read_b128 v[100:103], v193 offset:49152
	ds_read_b128 v[136:139], v193 offset:57344
	v_add_f32_e32 v148, 0, v231
	v_add_f32_e32 v148, v233, v148
	v_add_f32_e32 v148, v229, v148
	v_add_f32_e32 v148, v232, v148
	v_add_f32_e32 v148, v228, v148
	v_add_f32_e32 v148, v230, v148
	v_add_f32_e32 v148, v226, v148
	v_add_f32_e32 v148, v227, v148
	v_add_f32_e32 v148, v223, v148
	v_add_f32_e32 v148, v225, v148
	v_add_f32_e32 v148, v209, v148
	v_add_f32_e32 v148, v224, v148
	v_add_f32_e32 v148, v206, v148
	v_add_f32_e32 v148, v208, v148
	v_add_f32_e32 v148, v205, v148
	v_add_f32_e32 v148, v207, v148
	v_exp_f32_e32 v140, v152
	v_exp_f32_e32 v141, v153
	v_exp_f32_e32 v142, v180
	v_exp_f32_e32 v143, v181
	s_waitcnt lgkmcnt(3)
	v_mfma_f32_32x32x16_bf16 v[82:97], v[66:69], v[132:135], 0
	v_exp_f32_e32 v144, v160
	v_exp_f32_e32 v145, v161
	v_exp_f32_e32 v146, v154
	v_exp_f32_e32 v147, v155
	s_waitcnt lgkmcnt(2)
	v_mfma_f32_32x32x16_bf16 v[66:81], v[70:73], v[132:135], 0
	v_exp_f32_e32 v178, v178
	v_exp_f32_e32 v179, v179
	v_exp_f32_e32 v162, v162
	v_exp_f32_e32 v163, v163
	s_waitcnt lgkmcnt(1)
	v_mfma_f32_32x32x16_bf16 v[82:97], v[100:103], v[128:131], v[82:97]
	v_add_f32_e32 v148, v178, v148
	v_add_f32_e32 v148, v179, v148
	v_add_f32_e32 v148, v162, v148
	v_exp_f32_e32 v158, v158
	s_waitcnt lgkmcnt(0)
	v_mfma_f32_32x32x16_bf16 v[66:81], v[136:139], v[128:131], v[66:81]
	v_exp_f32_e32 v159, v159
	v_exp_f32_e32 v156, v156
	v_exp_f32_e32 v157, v157
	v_add_f32_e32 v148, v163, v148
	ds_read_b128 v[100:103], v194 offset:49152
	ds_read_b128 v[136:139], v194 offset:57344
	s_waitcnt lgkmcnt(1)
	v_mfma_f32_32x32x16_bf16 v[82:97], v[100:103], v[124:127], v[82:97]
	v_add_f32_e32 v148, v158, v148
	v_add_f32_e32 v148, v159, v148
	v_add_f32_e32 v148, v156, v148
	v_add_f32_e32 v148, v157, v148
	s_waitcnt lgkmcnt(0)
	v_mfma_f32_32x32x16_bf16 v[66:81], v[136:139], v[124:127], v[66:81]
	v_add_f32_e32 v148, v140, v148
	v_add_f32_e32 v148, v141, v148
	v_add_f32_e32 v148, v142, v148
	v_add_f32_e32 v148, v143, v148
	ds_read_b128 v[100:103], v195 offset:49152
	ds_read_b128 v[136:139], v195 offset:57344
	s_waitcnt lgkmcnt(1)
	v_mfma_f32_32x32x16_bf16 v[82:97], v[100:103], v[120:123], v[82:97]
	v_add_f32_e32 v148, v144, v148
	v_add_f32_e32 v148, v145, v148
	v_add_f32_e32 v148, v146, v148
	v_add_f32_e32 v199, v147, v148
	s_waitcnt lgkmcnt(0)
	v_mfma_f32_32x32x16_bf16 v[66:81], v[136:139], v[120:123], v[66:81]
	v_mov_b32_e32 v200, v199
	s_nop 1
	v_permlane32_swap_b32_e32 v199, v200
	v_cvt_pk_bf16_f32 v148, v231, v233
	v_cvt_pk_bf16_f32 v149, v229, v232
	v_cvt_pk_bf16_f32 v150, v228, v230
	ds_read_b128 v[100:103], v169 offset:49280
	ds_read_b128 v[136:139], v169 offset:57472
	s_waitcnt lgkmcnt(1)
	v_mfma_f32_32x32x16_bf16 v[82:97], v[100:103], v[116:119], v[82:97]
	v_cvt_pk_bf16_f32 v151, v226, v227
	v_cvt_pk_bf16_f32 v152, v223, v225
	v_cvt_pk_bf16_f32 v153, v209, v224
	s_waitcnt lgkmcnt(0)
	v_mfma_f32_32x32x16_bf16 v[66:81], v[136:139], v[116:119], v[66:81]
	v_cvt_pk_bf16_f32 v154, v206, v208
	v_cvt_pk_bf16_f32 v155, v205, v207
	v_cvt_pk_bf16_f32 v158, v158, v159
	ds_read_b128 v[100:103], v193 offset:49280
	ds_read_b128 v[136:139], v193 offset:57472
	s_waitcnt lgkmcnt(1)
	v_mfma_f32_32x32x16_bf16 v[82:97], v[100:103], v[112:115], v[82:97]
	v_cvt_pk_bf16_f32 v159, v156, v157
	v_cvt_pk_bf16_f32 v156, v178, v179
	v_cvt_pk_bf16_f32 v157, v162, v163
	s_waitcnt lgkmcnt(0)
	v_mfma_f32_32x32x16_bf16 v[66:81], v[136:139], v[112:115], v[66:81]
	v_cvt_pk_bf16_f32 v160, v140, v141
	v_cvt_pk_bf16_f32 v161, v142, v143
	v_cvt_pk_bf16_f32 v162, v144, v145
	ds_read_b128 v[100:103], v194 offset:49280
	ds_read_b128 v[136:139], v194 offset:57472
	s_waitcnt lgkmcnt(1)
	v_mfma_f32_32x32x16_bf16 v[82:97], v[100:103], v[108:111], v[82:97]
	v_cvt_pk_bf16_f32 v163, v146, v147
	s_nop 0
	v_permlane32_swap_b32_e32 v148, v150
	v_permlane32_swap_b32_e32 v149, v151
	s_waitcnt lgkmcnt(0)
	v_mfma_f32_32x32x16_bf16 v[66:81], v[136:139], v[108:111], v[66:81]
	v_permlane32_swap_b32_e32 v152, v154
	v_permlane32_swap_b32_e32 v153, v155
	v_permlane32_swap_b32_e32 v156, v158
	ds_read_b128 v[100:103], v195 offset:49280
	ds_read_b128 v[136:139], v195 offset:57472
	ds_read_b64_tr_b16 v[172:173], v185 offset:0
	ds_read_b64_tr_b16 v[174:175], v185 offset:0x800
	ds_read_b64_tr_b16 v[202:203], v185 offset:0x1000
	ds_read_b64_tr_b16 v[204:205], v185 offset:0x1800
	ds_read_b64_tr_b16 v[206:207], v185 offset:0x2000
	ds_read_b64_tr_b16 v[208:209], v185 offset:0x2800
	ds_read_b64_tr_b16 v[224:225], v185 offset:0x3000
	ds_read_b64_tr_b16 v[226:227], v185 offset:0x3800
	s_waitcnt lgkmcnt(9)
	v_mfma_f32_32x32x16_bf16 v[82:97], v[100:103], v[104:107], v[82:97]
	v_permlane32_swap_b32_e32 v157, v159
	v_permlane32_swap_b32_e32 v160, v162
	v_permlane32_swap_b32_e32 v161, v163
	s_waitcnt lgkmcnt(8)
	v_mfma_f32_32x32x16_bf16 v[66:81], v[136:139], v[104:107], v[66:81]
	v_add_u32_e32 v178, s7, v166
	v_add_u32_e32 v100, 1, v178
	v_add_u32_e32 v102, 33, v178
	v_ashrrev_i32_e32 v101, 31, v100
	v_ashrrev_i32_e32 v103, 31, v102
	v_lshlrev_b64 v[140:141], 8, v[100:101]
	v_lshlrev_b64 v[142:143], 8, v[102:103]
	v_lshl_add_u64 v[100:101], v[170:171], 0, v[140:141]
	v_lshl_add_u64 v[136:137], v[170:171], 0, v[142:143]
	v_lshl_add_u64 v[140:141], v[234:235], 0, v[140:141]
	v_lshl_add_u64 v[144:145], v[234:235], 0, v[142:143]
	global_load_dwordx4 v[100:103], v[100:101], off
	s_nop 0
	global_load_dwordx4 v[136:139], v[136:137], off
	s_nop 0
	s_mov_b32 m0, s32
	s_nop 0
	global_load_lds_dwordx4 v[140:141], off
	s_nop 0
	s_add_i32 m0, s32, 0x2000
	s_nop 0
	global_load_lds_dwordx4 v[144:145], off
	s_waitcnt lgkmcnt(0)
; __device__ __forceinline__ void mask_tile(f32x16& p0, f32x16& p1, int dq, unsigned W) {
;     const float NEG = -__builtin_inff();
; #pragma unroll
;     for (int r = 0; r < 16; ++r) {
;         const int c = (r & 3) + 8 * (r >> 2);
;         if ((unsigned)(dq - c) >= W) p0[r] = NEG;
;         if ((unsigned)(dq - c - 32) >= W) p1[r] = NEG;
;     }
; }
; template <int VB>
; __device__ __forceinline__ void pv_tile(f32x16* o, int vb0, bf16x8 pa0, bf16x8 pa1, bf16x8 pa2, bf16x8 pa3) {
;     ...
;     PV_D0(0); PV_D0(1); PV_D0(2); PV_D0(3);
	s_nop 0
	v_mfma_f32_32x32x16_bf16 v[50:65], v[148:151], v[172:175], v[50:65]
	ds_read_b64_tr_b16 v[172:173], v185 offset:0x200
	ds_read_b64_tr_b16 v[174:175], v185 offset:0xa00
	v_mfma_f32_32x32x16_bf16 v[50:65], v[152:155], v[202:205], v[50:65]
	ds_read_b64_tr_b16 v[202:203], v185 offset:0x1200
	ds_read_b64_tr_b16 v[204:205], v185 offset:0x1a00
	v_mfma_f32_32x32x16_bf16 v[50:65], v[156:159], v[206:209], v[50:65]
	ds_read_b64_tr_b16 v[206:207], v185 offset:0x2200
	ds_read_b64_tr_b16 v[208:209], v185 offset:0x2a00
	v_mfma_f32_32x32x16_bf16 v[50:65], v[160:163], v[224:227], v[50:65]
	ds_read_b64_tr_b16 v[224:225], v185 offset:0x3200
	ds_read_b64_tr_b16 v[226:227], v185 offset:0x3a00
	s_waitcnt lgkmcnt(0)
	v_mfma_f32_32x32x16_bf16 v[34:49], v[148:151], v[172:175], v[34:49]
	ds_read_b64_tr_b16 v[172:173], v185 offset:0x400
	ds_read_b64_tr_b16 v[174:175], v185 offset:0xc00
	v_mfma_f32_32x32x16_bf16 v[34:49], v[152:155], v[202:205], v[34:49]
	ds_read_b64_tr_b16 v[202:203], v185 offset:0x1400
	ds_read_b64_tr_b16 v[204:205], v185 offset:0x1c00
	v_mfma_f32_32x32x16_bf16 v[34:49], v[156:159], v[206:209], v[34:49]
	ds_read_b64_tr_b16 v[206:207], v185 offset:0x2400
	ds_read_b64_tr_b16 v[208:209], v185 offset:0x2c00
	v_mfma_f32_32x32x16_bf16 v[34:49], v[160:163], v[224:227], v[34:49]
	ds_read_b64_tr_b16 v[224:225], v185 offset:0x3400
	ds_read_b64_tr_b16 v[226:227], v185 offset:0x3c00
	s_waitcnt lgkmcnt(0)
	v_mfma_f32_32x32x16_bf16 v[18:33], v[148:151], v[172:175], v[18:33]
	ds_read_b64_tr_b16 v[172:173], v185 offset:0x600
	ds_read_b64_tr_b16 v[174:175], v185 offset:0xe00
	v_mfma_f32_32x32x16_bf16 v[18:33], v[152:155], v[202:205], v[18:33]
	ds_read_b64_tr_b16 v[202:203], v185 offset:0x1600
	ds_read_b64_tr_b16 v[204:205], v185 offset:0x1e00
	v_mfma_f32_32x32x16_bf16 v[18:33], v[156:159], v[206:209], v[18:33]
	ds_read_b64_tr_b16 v[206:207], v185 offset:0x2600
	ds_read_b64_tr_b16 v[208:209], v185 offset:0x2e00
	v_mfma_f32_32x32x16_bf16 v[18:33], v[160:163], v[224:227], v[18:33]
	ds_read_b64_tr_b16 v[224:225], v185 offset:0x3600
	ds_read_b64_tr_b16 v[226:227], v185 offset:0x3e00
	s_waitcnt lgkmcnt(0)
	v_mfma_f32_32x32x16_bf16 v[2:17], v[148:151], v[172:175], v[2:17]
	s_cmp_le_i32 s7, s6
	v_mfma_f32_32x32x16_bf16 v[2:17], v[152:155], v[202:205], v[2:17]
	v_mfma_f32_32x32x16_bf16 v[2:17], v[156:159], v[206:209], v[2:17]
	v_mfma_f32_32x32x16_bf16 v[2:17], v[160:163], v[224:227], v[2:17]
	s_cbranch_scc1 .LBB0_91
	v_add_u32_e32 v148, 0x4000007b, v197
	v_cmp_gt_u32_e32 vcc, 2.0, v148
	v_add_u32_e32 v148, 0x5b, v197
	s_nop 0
	v_cndmask_b32_e32 v82, v220, v82, vcc
	v_cmp_lt_u32_e32 vcc, s33, v148
	v_add_u32_e32 v148, 0x7a, v197
	s_nop 0
	v_cndmask_b32_e32 v66, v220, v66, vcc
	v_cmp_lt_u32_e32 vcc, s33, v148
	v_add_u32_e32 v148, 0x5a, v197
	s_nop 0
	v_cndmask_b32_e32 v83, v220, v83, vcc
	v_cmp_lt_u32_e32 vcc, s33, v148
	v_add_u32_e32 v148, 0x79, v197
	s_nop 0
	v_cndmask_b32_e32 v67, v220, v67, vcc
	v_cmp_lt_u32_e32 vcc, s33, v148
	v_add_u32_e32 v148, 0x59, v197
	s_nop 0
	v_cndmask_b32_e32 v84, v220, v84, vcc
	v_cmp_lt_u32_e32 vcc, s33, v148
	v_add_u32_e32 v148, 0x78, v197
	s_nop 0
	v_cndmask_b32_e32 v68, v220, v68, vcc
	v_cmp_lt_u32_e32 vcc, s33, v148
	v_add_u32_e32 v148, 0x58, v197
	s_nop 0
	v_cndmask_b32_e32 v85, v220, v85, vcc
	v_cmp_lt_u32_e32 vcc, s33, v148
	v_add_u32_e32 v148, 0x73, v197
	s_nop 0
	v_cndmask_b32_e32 v69, v220, v69, vcc
	v_cmp_lt_u32_e32 vcc, s33, v148
	v_add_u32_e32 v148, 0x53, v197
	s_nop 0
	v_cndmask_b32_e32 v86, v220, v86, vcc
	v_cmp_lt_u32_e32 vcc, s33, v148
	v_add_u32_e32 v148, 0x72, v197
	s_nop 0
	v_cndmask_b32_e32 v70, v220, v70, vcc
	v_cmp_lt_u32_e32 vcc, s33, v148
	v_add_u32_e32 v148, 0x52, v197
	s_nop 0
	v_cndmask_b32_e32 v87, v220, v87, vcc
	v_cmp_lt_u32_e32 vcc, s33, v148
	v_add_u32_e32 v148, 0x71, v197
	s_nop 0
	v_cndmask_b32_e32 v71, v220, v71, vcc
	v_cmp_lt_u32_e32 vcc, s33, v148
	v_add_u32_e32 v148, 0x51, v197
	s_nop 0
	v_cndmask_b32_e32 v88, v220, v88, vcc
	v_cmp_lt_u32_e32 vcc, s33, v148
	v_add_u32_e32 v148, 0x70, v197
	s_nop 0
	v_cndmask_b32_e32 v72, v220, v72, vcc
	v_cmp_lt_u32_e32 vcc, s33, v148
	v_add_u32_e32 v148, 0x50, v197
	s_nop 0
	v_cndmask_b32_e32 v89, v220, v89, vcc
	v_cmp_lt_u32_e32 vcc, s33, v148
	v_add_u32_e32 v148, 0x6b, v197
	s_nop 0
	v_cndmask_b32_e32 v73, v220, v73, vcc
	v_cmp_lt_u32_e32 vcc, s33, v148
	v_add_u32_e32 v148, 0x4b, v197
	s_nop 0
	v_cndmask_b32_e32 v90, v220, v90, vcc
	v_cmp_lt_u32_e32 vcc, s33, v148
	v_add_u32_e32 v148, 0x6a, v197
	s_nop 0
	v_cndmask_b32_e32 v74, v220, v74, vcc
	v_cmp_lt_u32_e32 vcc, s33, v148
	v_add_u32_e32 v148, 0x4a, v197
	s_nop 0
	v_cndmask_b32_e32 v91, v220, v91, vcc
	v_cmp_lt_u32_e32 vcc, s33, v148
	v_add_u32_e32 v148, 0x69, v197
	s_nop 0
	v_cndmask_b32_e32 v75, v220, v75, vcc
	v_cmp_lt_u32_e32 vcc, s33, v148
	v_add_u32_e32 v148, 0x49, v197
	s_nop 0
	v_cndmask_b32_e32 v92, v220, v92, vcc
	v_cmp_lt_u32_e32 vcc, s33, v148
	v_add_u32_e32 v148, 0x68, v197
	s_nop 0
	v_cndmask_b32_e32 v76, v220, v76, vcc
	v_cmp_lt_u32_e32 vcc, s33, v148
	v_add_u32_e32 v148, 0x48, v197
	s_nop 0
	v_cndmask_b32_e32 v93, v220, v93, vcc
	v_cmp_lt_u32_e32 vcc, s33, v148
	v_add_u32_e32 v148, 0x63, v197
	s_nop 0
	v_cndmask_b32_e32 v77, v220, v77, vcc
	v_cmp_lt_u32_e32 vcc, s33, v148
	v_add_u32_e32 v148, 0x43, v197
	s_nop 0
	v_cndmask_b32_e32 v94, v220, v94, vcc
	v_cmp_lt_u32_e32 vcc, s33, v148
	v_add_u32_e32 v148, 0x62, v197
	s_nop 0
	v_cndmask_b32_e32 v78, v220, v78, vcc
	v_cmp_lt_u32_e32 vcc, s33, v148
	v_add_u32_e32 v148, 0x42, v197
	s_nop 0
	v_cndmask_b32_e32 v95, v220, v95, vcc
	v_cmp_lt_u32_e32 vcc, s33, v148
	v_add_u32_e32 v148, 0x61, v197
	s_nop 0
	v_cndmask_b32_e32 v79, v220, v79, vcc
	v_cmp_lt_u32_e32 vcc, s33, v148
	v_add_u32_e32 v148, 0x41, v197
	s_nop 0
	v_cndmask_b32_e32 v96, v220, v96, vcc
	v_cmp_lt_u32_e32 vcc, s33, v148
	v_add_u32_e32 v148, 0x60, v197
	s_nop 0
	v_cndmask_b32_e32 v80, v220, v80, vcc
	v_cmp_lt_u32_e32 vcc, s33, v148
	v_add_u32_e32 v148, 64, v197
	s_nop 0
	v_cndmask_b32_e32 v97, v220, v97, vcc
	v_cmp_lt_u32_e32 vcc, s33, v148
	s_nop 1
	v_cndmask_b32_e32 v81, v220, v81, vcc
; __device__ __forceinline__ void partialSM(f32x16& p0, f32x16& p1, float& m_reg, float& mn, float& alpha, bool rs) {
;     float pmax = p0[0]; for (int r = 1; r < 16; ++r) pmax = fmaxf(pmax, p0[r]); for (int r = 0; r < 16; ++r) pmax = fmaxf(pmax, p1[r]);
;     if (!rs) pmax = -__builtin_inff();
;     { auto rr = __builtin_amdgcn_permlane32_swap(__float_as_uint(pmax), __float_as_uint(pmax), false, false);
;       pmax = fmaxf(__uint_as_float(rr[0]), __uint_as_float(rr[1])); }
;     constexpr float C2 = 1.4426950408889634f * SCALE;
;     if (__builtin_expect(__all((pmax - m_reg) * SCALE <= THR), 1)) { mn = m_reg; alpha = 1.f; }
;     else { mn = fmaxf(m_reg, pmax); alpha = __builtin_amdgcn_exp2f((m_reg - mn) * C2); m_reg = mn; }
;     const float mnL = rs ? -mn * C2 : -__builtin_inff();
;     for (int r = 0; r < 16; ++r) p0[r] = fmaf(p0[r], C2, mnL); for (int r = 0; r < 16; ++r) p1[r] = fmaf(p1[r], C2, mnL);
;     for (int r = 0; r < 16; ++r) p0[r] = __builtin_amdgcn_exp2f(p0[r]);
; }
.LBB0_91:
	s_add_i32 s0, s3, -2
	s_lshr_b32 s8, s0, 2
	s_cmp_ge_i32 s8, s44
	s_cselect_b64 s[0:1], -1, 0
	s_lshl_b32 s8, 1, s8
	v_and_b32_e32 v148, s8, v165
	v_cmp_ne_u32_e32 vcc, 0, v148
	v_max_f32_e32 v148, v83, v83
	v_max_f32_e32 v149, v82, v82
	v_max_f32_e32 v148, v149, v148
	v_max3_f32 v148, v148, v84, v85
	v_max3_f32 v148, v148, v86, v87
	v_max3_f32 v148, v148, v88, v89
	v_max3_f32 v148, v148, v90, v91
	v_max3_f32 v148, v148, v92, v93
	v_max3_f32 v148, v148, v94, v95
	v_max3_f32 v148, v148, v96, v97
	v_max3_f32 v148, v148, v66, v67
	v_max3_f32 v148, v148, v68, v69
	v_max3_f32 v148, v148, v70, v71
	v_max3_f32 v148, v148, v72, v73
	v_max3_f32 v148, v148, v74, v75
	v_max3_f32 v148, v148, v76, v77
	v_max3_f32 v148, v148, v78, v79
	s_or_b64 s[40:41], s[0:1], vcc
	v_max3_f32 v148, v148, v80, v81
	v_cndmask_b32_e64 v148, v220, v148, s[40:41]
	v_mov_b32_e32 v149, v148
	s_nop 1
	v_permlane32_swap_b32_e32 v148, v149
	v_max_f32_e32 v149, v149, v149
	v_max_f32_e32 v148, v148, v148
	v_max_f32_e32 v148, v148, v149
	v_sub_f32_e32 v149, v148, v198
	v_mul_f32_e32 v149, 0x3db504f3, v149
	v_cmp_ge_f32_e32 vcc, s91, v149
	v_max_f32_e32 v149, v198, v198
	v_max_f32_e32 v148, v149, v148
	v_sub_f32_e32 v149, v198, v148
	v_mul_f32_e32 v149, 0x3e0293ee, v149
	v_exp_f32_e32 v149, v149
	s_cmp_eq_u64 vcc, exec
	s_cselect_b64 s[42:43], -1, 0
	s_waitcnt vmcnt(0)
	v_cndmask_b32_e64 v202, v149, 1.0, s[42:43]
	v_cmp_gt_f32_e32 vcc, 1.0, v202
	s_waitcnt vmcnt(1)
	s_waitcnt vmcnt(0)
	s_waitcnt vmcnt(0)
	s_waitcnt vmcnt(0)
	s_cbranch_vccz .LBB0_95
	s_and_saveexec_b64 s[0:1], s[38:39]
	ds_write_b32 v187, v202 offset:128
	s_or_b64 exec, exec, s[0:1]
	s_waitcnt lgkmcnt(0)
	ds_read_b128 v[150:153], v186 offset:224
	ds_read_b128 v[154:157], v186 offset:192
	ds_read_b128 v[158:161], v186 offset:160
	ds_read_b128 v[172:175], v186 offset:128
	s_waitcnt lgkmcnt(3)
	v_pk_mul_f32 v[64:65], v[64:65], v[152:153]
	s_waitcnt lgkmcnt(2)
	v_pk_mul_f32 v[60:61], v[60:61], v[156:157]
	s_waitcnt lgkmcnt(1)
	v_pk_mul_f32 v[56:57], v[56:57], v[160:161]
	s_waitcnt lgkmcnt(0)
	v_pk_mul_f32 v[52:53], v[52:53], v[174:175]
	v_pk_mul_f32 v[62:63], v[62:63], v[150:151]
	v_pk_mul_f32 v[58:59], v[58:59], v[154:155]
	v_pk_mul_f32 v[54:55], v[54:55], v[158:159]
	v_pk_mul_f32 v[50:51], v[50:51], v[172:173]
	v_pk_mul_f32 v[48:49], v[48:49], v[152:153]
	v_pk_mul_f32 v[44:45], v[44:45], v[156:157]
	v_pk_mul_f32 v[40:41], v[40:41], v[160:161]
	v_pk_mul_f32 v[36:37], v[36:37], v[174:175]
	v_pk_mul_f32 v[46:47], v[46:47], v[150:151]
	v_pk_mul_f32 v[42:43], v[42:43], v[154:155]
	v_pk_mul_f32 v[38:39], v[38:39], v[158:159]
	v_pk_mul_f32 v[34:35], v[34:35], v[172:173]
	v_pk_mul_f32 v[32:33], v[32:33], v[152:153]
	v_pk_mul_f32 v[28:29], v[28:29], v[156:157]
	v_pk_mul_f32 v[24:25], v[24:25], v[160:161]
	v_pk_mul_f32 v[20:21], v[20:21], v[174:175]
	v_pk_mul_f32 v[30:31], v[30:31], v[150:151]
	v_pk_mul_f32 v[26:27], v[26:27], v[154:155]
	v_pk_mul_f32 v[22:23], v[22:23], v[158:159]
	v_pk_mul_f32 v[18:19], v[18:19], v[172:173]
	v_pk_mul_f32 v[16:17], v[16:17], v[152:153]
	v_pk_mul_f32 v[12:13], v[12:13], v[156:157]
	v_pk_mul_f32 v[8:9], v[8:9], v[160:161]
	v_pk_mul_f32 v[4:5], v[4:5], v[174:175]
	v_pk_mul_f32 v[14:15], v[14:15], v[150:151]
	v_pk_mul_f32 v[10:11], v[10:11], v[154:155]
	v_pk_mul_f32 v[6:7], v[6:7], v[158:159]
	v_pk_mul_f32 v[2:3], v[2:3], v[172:173]
.LBB0_95:
	v_cndmask_b32_e64 v179, v148, v198, s[42:43]
	v_mul_f32_e32 v148, 0xbe0293ee, v179
	v_cndmask_b32_e64 v180, v220, v148, s[40:41]
	v_fmamk_f32 v82, v82, 0x3e0293ee, v180
	v_fmamk_f32 v83, v83, 0x3e0293ee, v180
	v_fmamk_f32 v84, v84, 0x3e0293ee, v180
	v_fmamk_f32 v85, v85, 0x3e0293ee, v180
	v_fmamk_f32 v86, v86, 0x3e0293ee, v180
	v_fmamk_f32 v87, v87, 0x3e0293ee, v180
	v_fmamk_f32 v88, v88, 0x3e0293ee, v180
	v_fmamk_f32 v89, v89, 0x3e0293ee, v180
	v_fmamk_f32 v90, v90, 0x3e0293ee, v180
	v_fmamk_f32 v91, v91, 0x3e0293ee, v180
	v_fmamk_f32 v92, v92, 0x3e0293ee, v180
	v_fmamk_f32 v93, v93, 0x3e0293ee, v180
	v_fmamk_f32 v94, v94, 0x3e0293ee, v180
	v_fmamk_f32 v95, v95, 0x3e0293ee, v180
	v_fmamk_f32 v96, v96, 0x3e0293ee, v180
	v_fmamk_f32 v97, v97, 0x3e0293ee, v180
	v_exp_f32_e32 v148, v82
	v_exp_f32_e32 v163, v83
	v_exp_f32_e32 v149, v84
	v_exp_f32_e32 v162, v85
	v_exp_f32_e32 v150, v86
	v_exp_f32_e32 v161, v87
	v_exp_f32_e32 v151, v88
	v_exp_f32_e32 v160, v89
	v_exp_f32_e32 v152, v90
	v_exp_f32_e32 v159, v91
	v_exp_f32_e32 v153, v92
	v_exp_f32_e32 v158, v93
	v_exp_f32_e32 v154, v94
	v_exp_f32_e32 v157, v95
	v_exp_f32_e32 v155, v96
	v_exp_f32_e32 v156, v97
	v_fmamk_f32 v203, v73, 0x3e0293ee, v180
	v_fmamk_f32 v204, v74, 0x3e0293ee, v180
	v_fmamk_f32 v208, v66, 0x3e0293ee, v180
	v_fmamk_f32 v209, v67, 0x3e0293ee, v180
	v_fmamk_f32 v223, v68, 0x3e0293ee, v180
	v_fmamk_f32 v224, v69, 0x3e0293ee, v180
	v_fmamk_f32 v225, v70, 0x3e0293ee, v180
	v_fmamk_f32 v198, v71, 0x3e0293ee, v180
	v_fmamk_f32 v201, v72, 0x3e0293ee, v180
	v_fmamk_f32 v205, v75, 0x3e0293ee, v180
	v_fmamk_f32 v206, v76, 0x3e0293ee, v180
	v_fmamk_f32 v207, v77, 0x3e0293ee, v180
	v_fmamk_f32 v181, v78, 0x3e0293ee, v180
	v_fmamk_f32 v226, v79, 0x3e0293ee, v180
	v_fmamk_f32 v227, v80, 0x3e0293ee, v180
	v_fmac_f32_e32 v180, 0x3e0293ee, v81
	s_waitcnt lgkmcnt(0)
	s_barrier
; template <int KB>
; __device__ __forceinline__ void qkt(f32x16& p0, f32x16& p1, const char* K_lds, int r32, int hi, const bf16x8* qr) {
;     p0 = f32x16{}; p1 = f32x16{};
;     const char* kb[4];
; #pragma unroll
;     for (int dd = 0; dd < 4; ++dd) kb[dd] = K_lds + KB * SHM_K + KSWZ(r32, (dd * 16 + hi * 8) * 2);
; #pragma unroll
;     for (int d0 = 0; d0 < 8; ++d0) { const char* a = kb[d0 & 3] + (d0 >> 2) * 128;
;         bf16x8 b0 = *reinterpret_cast<const bf16x8*>(a);
;         bf16x8 b1 = *reinterpret_cast<const bf16x8*>(a + 32 * 256);
;         p0 = __builtin_amdgcn_mfma_f32_32x32x16_bf16(b0, qr[d0], p0, 0, 0, 0);
;         p1 = __builtin_amdgcn_mfma_f32_32x32x16_bf16(b1, qr[d0], p1, 0, 0, 0); }
	s_waitcnt vmcnt(0)
	ds_write_b128 v191, v[100:103]
	ds_write_b128 v192, v[136:139]
	ds_read_b128 v[66:69], v169 offset:32768
	ds_read_b128 v[70:73], v169 offset:40960
	ds_read_b128 v[172:175], v193 offset:32768
	ds_read_b128 v[228:231], v193 offset:40960
	v_exp_f32_e32 v198, v198
	v_exp_f32_e32 v201, v201
	v_exp_f32_e32 v214, v204
	v_exp_f32_e32 v205, v205
	v_exp_f32_e32 v206, v206
	v_exp_f32_e32 v207, v207
	v_exp_f32_e32 v181, v181
	v_exp_f32_e32 v215, v226
	v_exp_f32_e32 v216, v227
	v_exp_f32_e32 v180, v180
	v_exp_f32_e32 v218, v209
	v_exp_f32_e32 v209, v203
	v_add_f32_e32 v203, 0, v148
	v_add_f32_e32 v203, v163, v203
	v_add_f32_e32 v203, v149, v203
	v_add_f32_e32 v203, v162, v203
	v_add_f32_e32 v203, v150, v203
	v_add_f32_e32 v203, v161, v203
	v_add_f32_e32 v203, v151, v203
	v_add_f32_e32 v203, v160, v203
	s_waitcnt lgkmcnt(3)
	v_mfma_f32_32x32x16_bf16 v[82:97], v[66:69], v[132:135], 0
	v_add_f32_e32 v203, v152, v203
	v_add_f32_e32 v203, v159, v203
	v_add_f32_e32 v203, v153, v203
	v_add_f32_e32 v203, v158, v203
	s_waitcnt lgkmcnt(2)
	v_mfma_f32_32x32x16_bf16 v[66:81], v[70:73], v[132:135], 0
	v_exp_f32_e32 v217, v208
	v_add_f32_e32 v203, v154, v203
	v_add_f32_e32 v203, v157, v203
	v_exp_f32_e32 v219, v223
	s_waitcnt lgkmcnt(1)
	v_mfma_f32_32x32x16_bf16 v[82:97], v[172:175], v[128:131], v[82:97]
	v_add_f32_e32 v203, v155, v203
	v_exp_f32_e32 v222, v224
	v_add_f32_e32 v203, v156, v203
	v_exp_f32_e32 v208, v225
	s_waitcnt lgkmcnt(0)
	v_mfma_f32_32x32x16_bf16 v[66:81], v[228:231], v[128:131], v[66:81]
	v_add_f32_e32 v203, v217, v203
	v_add_f32_e32 v203, v218, v203
	v_add_f32_e32 v203, v219, v203
	v_add_f32_e32 v203, v222, v203
	ds_read_b128 v[172:175], v194 offset:32768
	ds_read_b128 v[228:231], v194 offset:40960
	s_waitcnt lgkmcnt(1)
	v_mfma_f32_32x32x16_bf16 v[82:97], v[172:175], v[124:127], v[82:97]
	v_add_f32_e32 v203, v208, v203
	v_add_f32_e32 v203, v198, v203
	v_add_f32_e32 v203, v201, v203
	v_add_f32_e32 v203, v209, v203
	s_waitcnt lgkmcnt(0)
	v_mfma_f32_32x32x16_bf16 v[66:81], v[228:231], v[124:127], v[66:81]
	v_add_f32_e32 v203, v214, v203
	v_add_f32_e32 v203, v205, v203
	v_add_f32_e32 v203, v206, v203
	v_add_f32_e32 v203, v207, v203
	ds_read_b128 v[172:175], v195 offset:32768
	ds_read_b128 v[228:231], v195 offset:40960
	s_waitcnt lgkmcnt(1)
	v_mfma_f32_32x32x16_bf16 v[82:97], v[172:175], v[120:123], v[82:97]
	v_add_f32_e32 v203, v181, v203
	v_add_f32_e32 v203, v215, v203
	v_add_f32_e32 v203, v216, v203
	v_add_f32_e32 v203, v180, v203
	s_waitcnt lgkmcnt(0)
	v_mfma_f32_32x32x16_bf16 v[66:81], v[228:231], v[120:123], v[66:81]
	v_mov_b32_e32 v204, v203
	v_cvt_pk_bf16_f32 v148, v148, v163
	v_cvt_pk_bf16_f32 v149, v149, v162
	v_cvt_pk_bf16_f32 v150, v150, v161
	ds_read_b128 v[172:175], v169 offset:32896
	ds_read_b128 v[228:231], v169 offset:41088
	s_waitcnt lgkmcnt(1)
	v_mfma_f32_32x32x16_bf16 v[82:97], v[172:175], v[116:119], v[82:97]
	v_cvt_pk_bf16_f32 v151, v151, v160
	v_cvt_pk_bf16_f32 v152, v152, v159
	v_cvt_pk_bf16_f32 v153, v153, v158
	v_cvt_pk_bf16_f32 v154, v154, v157
	s_waitcnt lgkmcnt(0)
	v_mfma_f32_32x32x16_bf16 v[66:81], v[228:231], v[116:119], v[66:81]
	v_cvt_pk_bf16_f32 v155, v155, v156
	v_cvt_pk_bf16_f32 v156, v217, v218
	v_cvt_pk_bf16_f32 v157, v219, v222
	ds_read_b128 v[172:175], v193 offset:32896
	ds_read_b128 v[228:231], v193 offset:41088
	s_waitcnt lgkmcnt(1)
	v_mfma_f32_32x32x16_bf16 v[82:97], v[172:175], v[112:115], v[82:97]
	v_cvt_pk_bf16_f32 v158, v208, v198
	v_cvt_pk_bf16_f32 v159, v201, v209
	v_cvt_pk_bf16_f32 v160, v214, v205
	s_waitcnt lgkmcnt(0)
	v_mfma_f32_32x32x16_bf16 v[66:81], v[228:231], v[112:115], v[66:81]
	v_cvt_pk_bf16_f32 v161, v206, v207
	v_cvt_pk_bf16_f32 v162, v181, v215
	v_cvt_pk_bf16_f32 v163, v216, v180
	ds_read_b128 v[172:175], v194 offset:32896
	ds_read_b128 v[228:231], v194 offset:41088
	s_waitcnt lgkmcnt(1)
	v_mfma_f32_32x32x16_bf16 v[82:97], v[172:175], v[108:111], v[82:97]
	s_nop 1
	v_permlane32_swap_b32_e32 v203, v204
	v_permlane32_swap_b32_e32 v148, v150
	v_permlane32_swap_b32_e32 v149, v151
	s_waitcnt lgkmcnt(0)
	v_mfma_f32_32x32x16_bf16 v[66:81], v[228:231], v[108:111], v[66:81]
	v_permlane32_swap_b32_e32 v152, v154
	v_permlane32_swap_b32_e32 v153, v155
	v_permlane32_swap_b32_e32 v156, v158
	ds_read_b128 v[172:175], v195 offset:32896
	ds_read_b128 v[228:231], v195 offset:41088
	ds_read_b64_tr_b16 v[206:207], v185 offset:0x5000
	ds_read_b64_tr_b16 v[208:209], v185 offset:0x5800
	ds_read_b64_tr_b16 v[224:225], v185 offset:0x6000
	ds_read_b64_tr_b16 v[226:227], v185 offset:0x6800
	s_waitcnt lgkmcnt(5)
	v_mfma_f32_32x32x16_bf16 v[82:97], v[172:175], v[104:107], v[82:97]
	v_permlane32_swap_b32_e32 v157, v159
	v_permlane32_swap_b32_e32 v160, v162
	v_permlane32_swap_b32_e32 v161, v163
	s_waitcnt lgkmcnt(4)
	v_mfma_f32_32x32x16_bf16 v[66:81], v[228:231], v[104:107], v[66:81]
	ds_read_b64_tr_b16 v[172:173], v185 offset:0x4000
	ds_read_b64_tr_b16 v[174:175], v185 offset:0x4800
	ds_read_b64_tr_b16 v[228:229], v185 offset:0x7000
	ds_read_b64_tr_b16 v[230:231], v185 offset:0x7800
	s_cmp_lt_u32 s3, s2
	s_cselect_b64 s[22:23], -1, 0
	s_cmp_ge_u32 s3, s2
	s_cbranch_scc1 .LBB0_97
	v_add_u32_e32 v242, 0x41, v178
	v_add_u32_e32 v246, 0x61, v178
	v_ashrrev_i32_e32 v243, 31, v242
	v_ashrrev_i32_e32 v247, 31, v246
	v_lshlrev_b64 v[140:141], 8, v[242:243]
	v_lshlrev_b64 v[142:143], 8, v[246:247]
	v_lshl_add_u64 v[242:243], v[170:171], 0, v[140:141]
	v_lshl_add_u64 v[246:247], v[170:171], 0, v[142:143]
	v_lshl_add_u64 v[140:141], v[234:235], 0, v[140:141]
	v_lshl_add_u64 v[144:145], v[234:235], 0, v[142:143]
	global_load_dwordx4 v[242:245], v[242:243], off
	s_nop 0
	global_load_dwordx4 v[246:249], v[246:247], off
	s_nop 0
	s_add_i32 m0, s32, 0x4000
	s_nop 0
	global_load_lds_dwordx4 v[140:141], off
	s_nop 0
	s_add_i32 m0, s32, 0x6000
	s_nop 0
	global_load_lds_dwordx4 v[144:145], off
	s_mov_b32 s100, 1

; __device__ __forceinline__ void partialSM(f32x16& p0, f32x16& p1, float& m_reg, float& mn, float& alpha, bool rs) {
;     float pmax = p0[0]; for (int r = 1; r < 16; ++r) pmax = fmaxf(pmax, p0[r]); for (int r = 0; r < 16; ++r) pmax = fmaxf(pmax, p1[r]);
;     if (!rs) pmax = -__builtin_inff();
;     { auto rr = __builtin_amdgcn_permlane32_swap(__float_as_uint(pmax), __float_as_uint(pmax), false, false);
;       pmax = fmaxf(__uint_as_float(rr[0]), __uint_as_float(rr[1])); }
;     constexpr float C2 = 1.4426950408889634f * SCALE;
;     if (__builtin_expect(__all((pmax - m_reg) * SCALE <= THR), 1)) { mn = m_reg; alpha = 1.f; }
;     else { mn = fmaxf(m_reg, pmax); alpha = __builtin_amdgcn_exp2f((m_reg - mn) * C2); m_reg = mn; }
.LBB0_99:
	s_add_i32 s0, s3, -1
	s_lshr_b32 s8, s0, 2
	s_cmp_ge_i32 s8, s44
	s_cselect_b64 s[0:1], -1, 0
	s_lshl_b32 s8, 1, s8
	v_and_b32_e32 v148, s8, v165
	v_cmp_ne_u32_e32 vcc, 0, v148
	v_max_f32_e32 v148, v83, v83
	v_max_f32_e32 v149, v82, v82
	v_max_f32_e32 v148, v149, v148
	v_max3_f32 v148, v148, v84, v85
	v_max3_f32 v148, v148, v86, v87
	v_max3_f32 v148, v148, v88, v89
	v_max3_f32 v148, v148, v90, v91
	v_max3_f32 v148, v148, v92, v93
	v_max3_f32 v148, v148, v94, v95
	v_max3_f32 v148, v148, v96, v97
	v_max3_f32 v148, v148, v66, v67
	v_max3_f32 v148, v148, v68, v69
	v_max3_f32 v148, v148, v70, v71
	v_max3_f32 v148, v148, v72, v73
	v_max3_f32 v148, v148, v74, v75
	v_max3_f32 v148, v148, v76, v77
	v_max3_f32 v148, v148, v78, v79
	v_max3_f32 v148, v148, v80, v81
	s_or_b64 s[40:41], s[0:1], vcc
	v_cndmask_b32_e64 v148, v220, v148, s[40:41]
	v_mov_b32_e32 v149, v148
	s_nop 1
	v_permlane32_swap_b32_e32 v148, v149
	v_max_f32_e32 v149, v149, v149
	v_max_f32_e32 v148, v148, v148
	v_max_f32_e32 v148, v148, v149
	v_sub_f32_e32 v149, v148, v179
	v_mul_f32_e32 v149, 0x3db504f3, v149
	v_cmp_ge_f32_e32 vcc, s91, v149
	s_cmp_eq_u64 vcc, exec
	s_cselect_b64 s[42:43], -1, 0
	s_andn2_b64 vcc, exec, s[22:23]
	s_cbranch_vccnz .LBB0_101
	s_waitcnt vmcnt(0)
	s_waitcnt vmcnt(1)
	s_waitcnt vmcnt(0)
	s_waitcnt vmcnt(0)
	s_waitcnt vmcnt(0)
